# GEMM main loop: fragment LDS base addresses formed once per tile, LDS-DMA destination (m0) formed in one scalar add each, required m0->DMA wait state restored
# speedup vs baseline: 1.0111x; 1.0010x over previous
; #define PG8_STAGE(bufoff, gbase, voff) do { _Pragma("unroll") for (int _i = 0; _i < 2; ++_i) \
;         __builtin_amdgcn_global_load_lds((const unsigned*)((const char*)(gbase) + (voff)[_i]), (LAS unsigned*)(lds + (bufoff) + ldsw + _i * 8192), 16, 0, 0); } while (0)
; #define PG8_LDA(dst, b, h) do { _Pragma("unroll") for (int m = 0; m < 4; ++m) _Pragma("unroll") for (int k = 0; k < 2; ++k) dst[m][k] = *(const LAS h16x8*)(lds + PG8_SA(b, h) + aoff + m * 2048 + k * 1024); } while (0)
; #define PG8_LDB(dst, b, h) do { _Pragma("unroll") for (int n = 0; n < 2; ++n) _Pragma("unroll") for (int k = 0; k < 2; ++k) dst[n][k] = *(const LAS h16x8*)(lds + PG8_SB(b, h) + boff + n * 2048 + k * 1024); } while (0)
; #define PG8_MMA(ai, bj, At, Bt) do { __builtin_amdgcn_s_setprio(1); _Pragma("unroll") for (int m = 0; m < 4; ++m) _Pragma("unroll") for (int n = 0; n < 2; ++n) _Pragma("unroll") for (int k = 0; k < 2; ++k) \
;         acc[ai][bj][m][n] = __builtin_amdgcn_mfma_f32_16x16x32_f16(Bt[n][k], At[m][k], acc[ai][bj][m][n], 0, 0, 0); __builtin_amdgcn_s_setprio(0); } while (0)
; #define PG8_WAIT_L(n) asm volatile("s_waitcnt lgkmcnt(" #n ")" ::: "memory")
; #define PG8_BAR __builtin_amdgcn_s_barrier()
; #define PG8_SCHED __builtin_amdgcn_sched_barrier(0)
; __device__ __forceinline__ void gemm_phase(LAS unsigned char* lds, const Gemm g, const StaticOrder& S, const Epi& E) {
;     ...
;             const char* a1 = cA + PG8_KOFF(t + 1);
;             const char* a2 = last ? nA : cA + PG8_KOFF(t + 2); const char* b2 = last ? nB : cB + (size_t)(t + 2) * kstep;
;             const char* a3 = a2 + kstep; const char* b3 = b2 + kstep;
;             PG8_LDB(B0, 0, 0); PG8_SCHED; PG8_LDA(At, 0, 0); PG8_STAGE(PG8_SA(1, 1), a1 + hstepA, voffA);
;             PG8_WAIT_L(8); PG8_BAR; PG8_WAIT_L(0); PG8_MMA(0, 0, At, B0); PG8_BAR; PG8_SCHED;
;     ...
; #pragma unroll
;         for (int a = 0; a < 2; ++a)
; #pragma unroll
;             for (int b = 0; b < 2; ++b)
; #pragma unroll
;                 for (int m = 0; m < 4; ++m)
; #pragma unroll
;                     for (int n = 0; n < 2; ++n) acc[a][b][m][n] = (f32x4){0.f, 0.f, 0.f, 0.f};
;         cur = nxt; cA = nA; cB = nB; ++ui;
.LBB0_761:
	s_add_u32 s0, s34, 0x80
	s_addc_u32 s1, s35, 0
	s_add_u32 s27, s36, 0x100
	v_mov_b32_e32 v0, 0
	s_addc_u32 s33, s37, 0
	s_mov_b32 s34, 0
	v_mov_b32_e32 v1, v0
	v_mov_b32_e32 v2, v0
	v_mov_b32_e32 v3, v0
	v_mov_b32_e32 v4, v0
	v_mov_b32_e32 v5, v0
	v_mov_b32_e32 v6, v0
	v_mov_b32_e32 v7, v0
	v_mov_b32_e32 v16, v0
	v_mov_b32_e32 v17, v0
	v_mov_b32_e32 v18, v0
	v_mov_b32_e32 v19, v0
	s_waitcnt vmcnt(0)
	v_mov_b32_e32 v20, v0
	v_mov_b32_e32 v21, v0
	v_mov_b32_e32 v22, v0
	v_mov_b32_e32 v23, v0
	v_mov_b32_e32 v32, v0
	v_mov_b32_e32 v33, v0
	v_mov_b32_e32 v34, v0
	v_mov_b32_e32 v35, v0
	v_mov_b32_e32 v36, v0
	v_mov_b32_e32 v37, v0
	v_mov_b32_e32 v38, v0
	v_mov_b32_e32 v39, v0
	v_mov_b32_e32 v48, v0
	v_mov_b32_e32 v49, v0
	v_mov_b32_e32 v50, v0
	v_mov_b32_e32 v51, v0
	v_mov_b32_e32 v52, v0
	v_mov_b32_e32 v53, v0
	v_mov_b32_e32 v54, v0
	v_mov_b32_e32 v55, v0
	v_mov_b32_e32 v8, v0
	v_mov_b32_e32 v9, v0
	v_mov_b32_e32 v10, v0
	v_mov_b32_e32 v11, v0
	v_mov_b32_e32 v12, v0
	v_mov_b32_e32 v13, v0
	v_mov_b32_e32 v14, v0
	v_mov_b32_e32 v15, v0
	v_mov_b32_e32 v24, v0
	v_mov_b32_e32 v25, v0
	v_mov_b32_e32 v26, v0
	v_mov_b32_e32 v27, v0
	v_mov_b32_e32 v28, v0
	v_mov_b32_e32 v29, v0
	v_mov_b32_e32 v30, v0
	v_mov_b32_e32 v31, v0
	v_mov_b32_e32 v40, v0
	v_mov_b32_e32 v41, v0
	v_mov_b32_e32 v42, v0
	v_mov_b32_e32 v43, v0
	v_mov_b32_e32 v44, v0
	v_mov_b32_e32 v45, v0
	v_mov_b32_e32 v46, v0
	v_mov_b32_e32 v47, v0
	v_mov_b32_e32 v56, v0
	v_mov_b32_e32 v57, v0
	v_mov_b32_e32 v58, v0
	v_mov_b32_e32 v59, v0
	v_mov_b32_e32 v60, v0
	v_mov_b32_e32 v61, v0
	v_mov_b32_e32 v62, v0
	v_mov_b32_e32 v63, v0
	v_mov_b32_e32 v64, v0
	v_mov_b32_e32 v65, v0
	v_mov_b32_e32 v66, v0
	v_mov_b32_e32 v67, v0
	v_mov_b32_e32 v68, v0
	v_mov_b32_e32 v69, v0
	v_mov_b32_e32 v70, v0
	v_mov_b32_e32 v71, v0
	v_mov_b32_e32 v80, v0
	v_mov_b32_e32 v81, v0
	v_mov_b32_e32 v82, v0
	v_mov_b32_e32 v83, v0
	v_mov_b32_e32 v84, v0
	v_mov_b32_e32 v85, v0
	v_mov_b32_e32 v86, v0
	v_mov_b32_e32 v87, v0
	v_mov_b32_e32 v96, v0
	v_mov_b32_e32 v97, v0
	v_mov_b32_e32 v98, v0
	v_mov_b32_e32 v99, v0
	v_mov_b32_e32 v100, v0
	v_mov_b32_e32 v101, v0
	v_mov_b32_e32 v102, v0
	v_mov_b32_e32 v103, v0
	v_mov_b32_e32 v112, v0
	v_mov_b32_e32 v113, v0
	v_mov_b32_e32 v114, v0
	v_mov_b32_e32 v115, v0
	v_mov_b32_e32 v116, v0
	v_mov_b32_e32 v117, v0
	v_mov_b32_e32 v118, v0
	v_mov_b32_e32 v119, v0
	v_mov_b32_e32 v72, v0
	v_mov_b32_e32 v73, v0
	v_mov_b32_e32 v74, v0
	v_mov_b32_e32 v75, v0
	v_mov_b32_e32 v76, v0
	v_mov_b32_e32 v77, v0
	v_mov_b32_e32 v78, v0
	v_mov_b32_e32 v79, v0
	v_mov_b32_e32 v88, v0
	v_mov_b32_e32 v89, v0
	v_mov_b32_e32 v90, v0
	v_mov_b32_e32 v91, v0
	v_mov_b32_e32 v92, v0
	v_mov_b32_e32 v93, v0
	v_mov_b32_e32 v94, v0
	v_mov_b32_e32 v95, v0
	v_mov_b32_e32 v104, v0
	v_mov_b32_e32 v105, v0
	v_mov_b32_e32 v106, v0
	v_mov_b32_e32 v107, v0
	v_mov_b32_e32 v108, v0
	v_mov_b32_e32 v109, v0
	v_mov_b32_e32 v110, v0
	v_mov_b32_e32 v111, v0
	v_mov_b32_e32 v120, v0
	v_mov_b32_e32 v121, v0
	v_mov_b32_e32 v122, v0
	v_mov_b32_e32 v123, v0
	v_mov_b32_e32 v124, v0
	v_mov_b32_e32 v125, v0
	v_mov_b32_e32 v126, v0
	v_mov_b32_e32 v127, v0
	v_add_u32_e32 v224, 0x10000, v238
	v_add_u32_e32 v225, 0x14000, v238
	v_add_u32_e32 v241, 0x18000, v238
	v_add_u32_e32 v248, 0x1c000, v238
	s_cmpk_gt_u32 s57, 0xff
	s_cbranch_scc1 .Lprio_skip
	s_setprio 1
.Lprio_skip:
.LBB0_762:
	s_cmp_gt_u32 s34, 15
	s_cselect_b64 s[36:37], -1, 0
	s_and_b64 s[36:37], s[6:7], s[36:37]
	s_and_b64 s[36:37], s[36:37], exec
	s_cselect_b32 s42, 0xfffff000, 0
	s_cselect_b32 s43, -1, 0
	s_add_i32 s38, s34, 2
	s_cmp_gt_u32 s34, 13
	s_cselect_b64 s[36:37], -1, 0
	s_and_b64 s[36:37], s[6:7], s[36:37]
	s_and_b64 s[36:37], s[36:37], exec
	s_cselect_b32 s36, 0xfffff000, 0
	s_cselect_b32 s35, -1, 0
	s_add_u32 s36, s0, s36
	s_addc_u32 s35, s1, s35
	s_add_u32 s36, s36, 0x80
	s_addc_u32 s35, s35, 0
	ds_read_b128 v[128:131], v224
	ds_read_b128 v[132:135], v224 offset:1024
	ds_read_b128 v[136:139], v224 offset:2048
	ds_read_b128 v[140:143], v224 offset:3072
	s_cmp_eq_u32 s66, s34
	s_cselect_b32 s34, s4, s36
	s_cselect_b32 s35, s5, s35
	s_cselect_b32 s37, s29, s33
	s_cselect_b32 s36, s28, s27
	s_add_u32 s86, s0, s42
	s_addc_u32 s87, s1, s43
	s_add_i32 m0, s58, 0xc000
	ds_read_b128 v[144:147], v239
	ds_read_b128 v[148:151], v239 offset:1024
	ds_read_b128 v[152:155], v239 offset:2048
	ds_read_b128 v[156:159], v239 offset:3072
	ds_read_b128 v[160:163], v239 offset:4096
	ds_read_b128 v[164:167], v239 offset:5120
	ds_read_b128 v[168:171], v239 offset:6144
	ds_read_b128 v[172:175], v239 offset:7168
	global_load_lds_dwordx4 v212, s[86:87]
	s_add_i32 m0, s58, 0xe000
	s_nop 0
	global_load_lds_dwordx4 v214, s[86:87]
	s_waitcnt lgkmcnt(8)
	s_barrier
	s_waitcnt lgkmcnt(0)
	s_waitcnt lgkmcnt(0)
	v_mfma_f32_16x16x32_f16 v[124:127], v[128:131], v[144:147], v[124:127]
	v_mfma_f32_16x16x32_f16 v[120:123], v[136:139], v[144:147], v[120:123]
	v_mfma_f32_16x16x32_f16 v[108:111], v[128:131], v[152:155], v[108:111]
	v_mfma_f32_16x16x32_f16 v[104:107], v[136:139], v[152:155], v[104:107]
	v_mfma_f32_16x16x32_f16 v[92:95], v[128:131], v[160:163], v[92:95]
	v_mfma_f32_16x16x32_f16 v[88:91], v[136:139], v[160:163], v[88:91]
	v_mfma_f32_16x16x32_f16 v[76:79], v[128:131], v[168:171], v[76:79]
	v_mfma_f32_16x16x32_f16 v[72:75], v[136:139], v[168:171], v[72:75]
	v_mfma_f32_16x16x32_f16 v[124:127], v[132:135], v[148:151], v[124:127]
	v_mfma_f32_16x16x32_f16 v[120:123], v[140:143], v[148:151], v[120:123]
	v_mfma_f32_16x16x32_f16 v[108:111], v[132:135], v[156:159], v[108:111]
	v_mfma_f32_16x16x32_f16 v[104:107], v[140:143], v[156:159], v[104:107]
	v_mfma_f32_16x16x32_f16 v[92:95], v[132:135], v[164:167], v[92:95]
	v_mfma_f32_16x16x32_f16 v[88:91], v[140:143], v[164:167], v[88:91]
	v_mfma_f32_16x16x32_f16 v[76:79], v[132:135], v[172:175], v[76:79]
	v_mfma_f32_16x16x32_f16 v[72:75], v[140:143], v[172:175], v[72:75]
	s_barrier
; #define PG8_STAGE(bufoff, gbase, voff) do { _Pragma("unroll") for (int _i = 0; _i < 2; ++_i) \
;         __builtin_amdgcn_global_load_lds((const unsigned*)((const char*)(gbase) + (voff)[_i]), (LAS unsigned*)(lds + (bufoff) + ldsw + _i * 8192), 16, 0, 0); } while (0)
; #define PG8_LDA(dst, b, h) do { _Pragma("unroll") for (int m = 0; m < 4; ++m) _Pragma("unroll") for (int k = 0; k < 2; ++k) dst[m][k] = *(const LAS h16x8*)(lds + PG8_SA(b, h) + aoff + m * 2048 + k * 1024); } while (0)
; #define PG8_LDB(dst, b, h) do { _Pragma("unroll") for (int n = 0; n < 2; ++n) _Pragma("unroll") for (int k = 0; k < 2; ++k) dst[n][k] = *(const LAS h16x8*)(lds + PG8_SB(b, h) + boff + n * 2048 + k * 1024); } while (0)
; #define PG8_MMA(ai, bj, At, Bt) do { __builtin_amdgcn_s_setprio(1); _Pragma("unroll") for (int m = 0; m < 4; ++m) _Pragma("unroll") for (int n = 0; n < 2; ++n) _Pragma("unroll") for (int k = 0; k < 2; ++k) \
;         acc[ai][bj][m][n] = __builtin_amdgcn_mfma_f32_16x16x32_f16(Bt[n][k], At[m][k], acc[ai][bj][m][n], 0, 0, 0); __builtin_amdgcn_s_setprio(0); } while (0)
; #define PG8_WAIT_V(n) asm volatile("s_waitcnt vmcnt(" #n ")" ::: "memory")
; #define PG8_WAIT_L(n) asm volatile("s_waitcnt lgkmcnt(" #n ")" ::: "memory")
; #define PG8_BAR __builtin_amdgcn_s_barrier()
; #define PG8_SCHED __builtin_amdgcn_sched_barrier(0)
; __device__ __forceinline__ void gemm_phase(LAS unsigned char* lds, const Gemm g, const StaticOrder& S, const Epi& E) {
;     ...
;             PG8_LDB(B1, 0, 1); PG8_STAGE(PG8_SB(0, 0), b2, voffB);
;             PG8_BAR; PG8_WAIT_L(0); PG8_MMA(0, 1, At, B1); PG8_BAR;
;             PG8_LDA(At, 0, 1); PG8_STAGE(PG8_SA(0, 0), a2, voffA);
;             PG8_BAR; PG8_WAIT_L(0); PG8_MMA(1, 0, At, B0); PG8_BAR; PG8_SCHED;
;             PG8_STAGE(PG8_SB(0, 1), b2 + hstepB, voffB);
;             PG8_WAIT_V(6); PG8_BAR; PG8_MMA(1, 1, At, B1); PG8_BAR;
;             PG8_LDB(B0, 1, 0); PG8_SCHED; PG8_LDA(At, 1, 0); PG8_STAGE(PG8_SA(0, 1), a2 + hstepA, voffA);
;             PG8_WAIT_L(8); PG8_BAR; PG8_WAIT_L(0); PG8_MMA(0, 0, At, B0); PG8_BAR; PG8_SCHED;
;             PG8_LDB(B1, 1, 1); PG8_STAGE(PG8_SB(1, 0), b3, voffB);
	s_add_u32 s86, s36, 0x80
	s_addc_u32 s87, s37, 0
	s_add_i32 m0, s31, 0x10000
	ds_read_b128 v[176:179], v225
	ds_read_b128 v[180:183], v225 offset:1024
	ds_read_b128 v[184:187], v225 offset:2048
	ds_read_b128 v[188:191], v225 offset:3072
	global_load_lds_dwordx4 v206, s[36:37]
	s_add_i32 m0, s31, 0x12000
	s_nop 0
	global_load_lds_dwordx4 v210, s[36:37]
	s_barrier
	s_waitcnt lgkmcnt(0)
	s_waitcnt lgkmcnt(0)
	v_mfma_f32_16x16x32_f16 v[116:119], v[176:179], v[144:147], v[116:119]
	v_mfma_f32_16x16x32_f16 v[112:115], v[184:187], v[144:147], v[112:115]
	v_mfma_f32_16x16x32_f16 v[100:103], v[176:179], v[152:155], v[100:103]
	v_mfma_f32_16x16x32_f16 v[96:99], v[184:187], v[152:155], v[96:99]
	v_mfma_f32_16x16x32_f16 v[84:87], v[176:179], v[160:163], v[84:87]
	v_mfma_f32_16x16x32_f16 v[80:83], v[184:187], v[160:163], v[80:83]
	v_mfma_f32_16x16x32_f16 v[68:71], v[176:179], v[168:171], v[68:71]
	v_mfma_f32_16x16x32_f16 v[64:67], v[184:187], v[168:171], v[64:67]
	v_mfma_f32_16x16x32_f16 v[116:119], v[180:183], v[148:151], v[116:119]
	v_mfma_f32_16x16x32_f16 v[112:115], v[188:191], v[148:151], v[112:115]
	v_mfma_f32_16x16x32_f16 v[100:103], v[180:183], v[156:159], v[100:103]
	v_mfma_f32_16x16x32_f16 v[96:99], v[188:191], v[156:159], v[96:99]
	v_mfma_f32_16x16x32_f16 v[84:87], v[180:183], v[164:167], v[84:87]
	v_mfma_f32_16x16x32_f16 v[80:83], v[188:191], v[164:167], v[80:83]
	v_mfma_f32_16x16x32_f16 v[68:71], v[180:183], v[172:175], v[68:71]
	v_mfma_f32_16x16x32_f16 v[64:67], v[188:191], v[172:175], v[64:67]
	s_mov_b32 m0, s58
	s_add_u32 s88, s34, 0x80
	s_addc_u32 s89, s35, 0
	s_barrier
	ds_read_b128 v[144:147], v239 offset:16384
	ds_read_b128 v[148:151], v239 offset:17408
	ds_read_b128 v[152:155], v239 offset:18432
	ds_read_b128 v[156:159], v239 offset:19456
	ds_read_b128 v[160:163], v239 offset:20480
	ds_read_b128 v[164:167], v239 offset:21504
	ds_read_b128 v[168:171], v239 offset:22528
	ds_read_b128 v[172:175], v239 offset:23552
	global_load_lds_dwordx4 v204, s[34:35]
	s_mov_b32 m0, s59
	s_nop 0
	global_load_lds_dwordx4 v208, s[34:35]
	s_barrier
	s_waitcnt lgkmcnt(0)
	s_waitcnt lgkmcnt(0)
	v_mfma_f32_16x16x32_f16 v[60:63], v[128:131], v[144:147], v[60:63]
	v_mfma_f32_16x16x32_f16 v[56:59], v[136:139], v[144:147], v[56:59]
	v_mfma_f32_16x16x32_f16 v[44:47], v[128:131], v[152:155], v[44:47]
	v_mfma_f32_16x16x32_f16 v[40:43], v[136:139], v[152:155], v[40:43]
	v_mfma_f32_16x16x32_f16 v[28:31], v[128:131], v[160:163], v[28:31]
	v_mfma_f32_16x16x32_f16 v[24:27], v[136:139], v[160:163], v[24:27]
	v_mfma_f32_16x16x32_f16 v[12:15], v[128:131], v[168:171], v[12:15]
	v_mfma_f32_16x16x32_f16 v[8:11], v[136:139], v[168:171], v[8:11]
	v_mfma_f32_16x16x32_f16 v[60:63], v[132:135], v[148:151], v[60:63]
	v_mfma_f32_16x16x32_f16 v[56:59], v[140:143], v[148:151], v[56:59]
	v_mfma_f32_16x16x32_f16 v[44:47], v[132:135], v[156:159], v[44:47]
	v_mfma_f32_16x16x32_f16 v[40:43], v[140:143], v[156:159], v[40:43]
	v_mfma_f32_16x16x32_f16 v[28:31], v[132:135], v[164:167], v[28:31]
	v_mfma_f32_16x16x32_f16 v[24:27], v[140:143], v[164:167], v[24:27]
	v_mfma_f32_16x16x32_f16 v[12:15], v[132:135], v[172:175], v[12:15]
	v_mfma_f32_16x16x32_f16 v[8:11], v[140:143], v[172:175], v[8:11]
	s_barrier
	s_add_u32 s36, s36, s18
	s_addc_u32 s37, s37, s19
	s_add_u32 s96, s36, 0x80
	s_addc_u32 s97, s37, 0
	s_add_i32 m0, s31, 0x14000
	s_nop 0
	global_load_lds_dwordx4 v206, s[36:37]
	s_add_i32 m0, s31, 0x16000
	s_nop 0
	global_load_lds_dwordx4 v210, s[36:37]
	s_waitcnt vmcnt(6)
	s_barrier
	v_mfma_f32_16x16x32_f16 v[52:55], v[176:179], v[144:147], v[52:55]
	v_mfma_f32_16x16x32_f16 v[48:51], v[184:187], v[144:147], v[48:51]
	v_mfma_f32_16x16x32_f16 v[36:39], v[176:179], v[152:155], v[36:39]
	v_mfma_f32_16x16x32_f16 v[32:35], v[184:187], v[152:155], v[32:35]
	v_mfma_f32_16x16x32_f16 v[20:23], v[176:179], v[160:163], v[20:23]
	v_mfma_f32_16x16x32_f16 v[16:19], v[184:187], v[160:163], v[16:19]
	v_mfma_f32_16x16x32_f16 v[4:7], v[176:179], v[168:171], v[4:7]
	v_mfma_f32_16x16x32_f16 v[0:3], v[184:187], v[168:171], v[0:3]
	v_mfma_f32_16x16x32_f16 v[52:55], v[180:183], v[148:151], v[52:55]
	v_mfma_f32_16x16x32_f16 v[48:51], v[188:191], v[148:151], v[48:51]
	v_mfma_f32_16x16x32_f16 v[36:39], v[180:183], v[156:159], v[36:39]
	v_mfma_f32_16x16x32_f16 v[32:35], v[188:191], v[156:159], v[32:35]
	v_mfma_f32_16x16x32_f16 v[20:23], v[180:183], v[164:167], v[20:23]
	v_mfma_f32_16x16x32_f16 v[16:19], v[188:191], v[164:167], v[16:19]
	v_mfma_f32_16x16x32_f16 v[4:7], v[180:183], v[172:175], v[4:7]
	v_mfma_f32_16x16x32_f16 v[0:3], v[188:191], v[172:175], v[0:3]
	s_barrier
	ds_read_b128 v[128:131], v241
	ds_read_b128 v[132:135], v241 offset:1024
	ds_read_b128 v[136:139], v241 offset:2048
	ds_read_b128 v[140:143], v241 offset:3072
	s_add_u32 s34, s34, s16
	s_addc_u32 s35, s35, s17
	s_mov_b32 m0, s60
	ds_read_b128 v[144:147], v239 offset:32768
	ds_read_b128 v[148:151], v239 offset:33792
	ds_read_b128 v[152:155], v239 offset:34816
	ds_read_b128 v[156:159], v239 offset:35840
	ds_read_b128 v[160:163], v239 offset:36864
	ds_read_b128 v[164:167], v239 offset:37888
	ds_read_b128 v[168:171], v239 offset:38912
	ds_read_b128 v[172:175], v239 offset:39936
	global_load_lds_dwordx4 v204, s[34:35]
	s_mov_b32 m0, s61
	s_nop 0
	global_load_lds_dwordx4 v208, s[34:35]
	s_waitcnt lgkmcnt(8)
	s_barrier
; #define PG8_STAGE(bufoff, gbase, voff) do { _Pragma("unroll") for (int _i = 0; _i < 2; ++_i) \
;         __builtin_amdgcn_global_load_lds((const unsigned*)((const char*)(gbase) + (voff)[_i]), (LAS unsigned*)(lds + (bufoff) + ldsw + _i * 8192), 16, 0, 0); } while (0)
; #define PG8_LDA(dst, b, h) do { _Pragma("unroll") for (int m = 0; m < 4; ++m) _Pragma("unroll") for (int k = 0; k < 2; ++k) dst[m][k] = *(const LAS h16x8*)(lds + PG8_SA(b, h) + aoff + m * 2048 + k * 1024); } while (0)
; #define PG8_LDB(dst, b, h) do { _Pragma("unroll") for (int n = 0; n < 2; ++n) _Pragma("unroll") for (int k = 0; k < 2; ++k) dst[n][k] = *(const LAS h16x8*)(lds + PG8_SB(b, h) + boff + n * 2048 + k * 1024); } while (0)
; #define PG8_MMA(ai, bj, At, Bt) do { __builtin_amdgcn_s_setprio(1); _Pragma("unroll") for (int m = 0; m < 4; ++m) _Pragma("unroll") for (int n = 0; n < 2; ++n) _Pragma("unroll") for (int k = 0; k < 2; ++k) \
;         acc[ai][bj][m][n] = __builtin_amdgcn_mfma_f32_16x16x32_f16(Bt[n][k], At[m][k], acc[ai][bj][m][n], 0, 0, 0); __builtin_amdgcn_s_setprio(0); } while (0)
; #define PG8_WAIT_V(n) asm volatile("s_waitcnt vmcnt(" #n ")" ::: "memory")
; #define PG8_WAIT_L(n) asm volatile("s_waitcnt lgkmcnt(" #n ")" ::: "memory")
; #define PG8_BAR __builtin_amdgcn_s_barrier()
; #define PG8_SCHED __builtin_amdgcn_sched_barrier(0)
; __device__ __forceinline__ void gemm_phase(LAS unsigned char* lds, const Gemm g, const StaticOrder& S, const Epi& E) {
;     ...
;             PG8_LDB(B1, 1, 1); PG8_STAGE(PG8_SB(1, 0), b3, voffB);
;             PG8_BAR; PG8_WAIT_L(0); PG8_MMA(0, 1, At, B1); PG8_BAR;
;             PG8_LDA(At, 1, 1); PG8_STAGE(PG8_SA(1, 0), a3, voffA);
;             PG8_BAR; PG8_WAIT_L(0); PG8_MMA(1, 0, At, B0); PG8_BAR; PG8_SCHED;
;             PG8_STAGE(PG8_SB(1, 1), b3 + hstepB, voffB);
;             PG8_WAIT_V(6); PG8_BAR; PG8_MMA(1, 1, At, B1); PG8_BAR;
	s_waitcnt lgkmcnt(0)
	s_waitcnt lgkmcnt(0)
	v_mfma_f32_16x16x32_f16 v[124:127], v[128:131], v[144:147], v[124:127]
	v_mfma_f32_16x16x32_f16 v[120:123], v[136:139], v[144:147], v[120:123]
	v_mfma_f32_16x16x32_f16 v[108:111], v[128:131], v[152:155], v[108:111]
	v_mfma_f32_16x16x32_f16 v[104:107], v[136:139], v[152:155], v[104:107]
	v_mfma_f32_16x16x32_f16 v[92:95], v[128:131], v[160:163], v[92:95]
	v_mfma_f32_16x16x32_f16 v[88:91], v[136:139], v[160:163], v[88:91]
	v_mfma_f32_16x16x32_f16 v[76:79], v[128:131], v[168:171], v[76:79]
	v_mfma_f32_16x16x32_f16 v[72:75], v[136:139], v[168:171], v[72:75]
	v_mfma_f32_16x16x32_f16 v[124:127], v[132:135], v[148:151], v[124:127]
	v_mfma_f32_16x16x32_f16 v[120:123], v[140:143], v[148:151], v[120:123]
	v_mfma_f32_16x16x32_f16 v[108:111], v[132:135], v[156:159], v[108:111]
	v_mfma_f32_16x16x32_f16 v[104:107], v[140:143], v[156:159], v[104:107]
	v_mfma_f32_16x16x32_f16 v[92:95], v[132:135], v[164:167], v[92:95]
	v_mfma_f32_16x16x32_f16 v[88:91], v[140:143], v[164:167], v[88:91]
	v_mfma_f32_16x16x32_f16 v[76:79], v[132:135], v[172:175], v[76:79]
	v_mfma_f32_16x16x32_f16 v[72:75], v[140:143], v[172:175], v[72:75]
	s_barrier
	s_add_i32 m0, s31, 0x18000
	ds_read_b128 v[176:179], v248
	ds_read_b128 v[180:183], v248 offset:1024
	ds_read_b128 v[184:187], v248 offset:2048
	ds_read_b128 v[188:191], v248 offset:3072
	global_load_lds_dwordx4 v206, s[86:87]
	s_add_i32 m0, s31, 0x1a000
	s_nop 0
	global_load_lds_dwordx4 v210, s[86:87]
	s_barrier
	s_waitcnt lgkmcnt(0)
	s_waitcnt lgkmcnt(0)
	v_mfma_f32_16x16x32_f16 v[116:119], v[176:179], v[144:147], v[116:119]
	v_mfma_f32_16x16x32_f16 v[112:115], v[184:187], v[144:147], v[112:115]
	v_mfma_f32_16x16x32_f16 v[100:103], v[176:179], v[152:155], v[100:103]
	v_mfma_f32_16x16x32_f16 v[96:99], v[184:187], v[152:155], v[96:99]
	v_mfma_f32_16x16x32_f16 v[84:87], v[176:179], v[160:163], v[84:87]
	v_mfma_f32_16x16x32_f16 v[80:83], v[184:187], v[160:163], v[80:83]
	v_mfma_f32_16x16x32_f16 v[68:71], v[176:179], v[168:171], v[68:71]
	v_mfma_f32_16x16x32_f16 v[64:67], v[184:187], v[168:171], v[64:67]
	v_mfma_f32_16x16x32_f16 v[116:119], v[180:183], v[148:151], v[116:119]
	v_mfma_f32_16x16x32_f16 v[112:115], v[188:191], v[148:151], v[112:115]
	v_mfma_f32_16x16x32_f16 v[100:103], v[180:183], v[156:159], v[100:103]
	v_mfma_f32_16x16x32_f16 v[96:99], v[188:191], v[156:159], v[96:99]
	v_mfma_f32_16x16x32_f16 v[84:87], v[180:183], v[164:167], v[84:87]
	v_mfma_f32_16x16x32_f16 v[80:83], v[188:191], v[164:167], v[80:83]
	v_mfma_f32_16x16x32_f16 v[68:71], v[180:183], v[172:175], v[68:71]
	v_mfma_f32_16x16x32_f16 v[64:67], v[188:191], v[172:175], v[64:67]
	s_mov_b32 m0, s62
	s_barrier
	ds_read_b128 v[144:147], v239 offset:49152
	ds_read_b128 v[148:151], v239 offset:50176
	ds_read_b128 v[152:155], v239 offset:51200
	ds_read_b128 v[156:159], v239 offset:52224
	ds_read_b128 v[160:163], v239 offset:53248
	ds_read_b128 v[164:167], v239 offset:54272
	ds_read_b128 v[168:171], v239 offset:55296
	ds_read_b128 v[172:175], v239 offset:56320
	global_load_lds_dwordx4 v204, s[88:89]
	s_mov_b32 m0, s63
	s_nop 0
	global_load_lds_dwordx4 v208, s[88:89]
	s_barrier
	s_waitcnt lgkmcnt(0)
	s_waitcnt lgkmcnt(0)
	v_mfma_f32_16x16x32_f16 v[60:63], v[128:131], v[144:147], v[60:63]
	v_mfma_f32_16x16x32_f16 v[56:59], v[136:139], v[144:147], v[56:59]
	v_mfma_f32_16x16x32_f16 v[44:47], v[128:131], v[152:155], v[44:47]
	v_mfma_f32_16x16x32_f16 v[40:43], v[136:139], v[152:155], v[40:43]
	v_mfma_f32_16x16x32_f16 v[28:31], v[128:131], v[160:163], v[28:31]
	v_mfma_f32_16x16x32_f16 v[24:27], v[136:139], v[160:163], v[24:27]
	v_mfma_f32_16x16x32_f16 v[12:15], v[128:131], v[168:171], v[12:15]
	v_mfma_f32_16x16x32_f16 v[8:11], v[136:139], v[168:171], v[8:11]
	v_mfma_f32_16x16x32_f16 v[60:63], v[132:135], v[148:151], v[60:63]
	v_mfma_f32_16x16x32_f16 v[56:59], v[140:143], v[148:151], v[56:59]
	v_mfma_f32_16x16x32_f16 v[44:47], v[132:135], v[156:159], v[44:47]
	v_mfma_f32_16x16x32_f16 v[40:43], v[140:143], v[156:159], v[40:43]
	v_mfma_f32_16x16x32_f16 v[28:31], v[132:135], v[164:167], v[28:31]
	v_mfma_f32_16x16x32_f16 v[24:27], v[140:143], v[164:167], v[24:27]
	v_mfma_f32_16x16x32_f16 v[12:15], v[132:135], v[172:175], v[12:15]
	v_mfma_f32_16x16x32_f16 v[8:11], v[140:143], v[172:175], v[8:11]
	s_barrier
	s_add_i32 m0, s31, 0x1c000
	s_nop 0
	global_load_lds_dwordx4 v206, s[96:97]
	s_add_i32 m0, s31, 0x1e000
	s_nop 0
	global_load_lds_dwordx4 v210, s[96:97]
	s_waitcnt vmcnt(6)
	s_barrier
	v_mfma_f32_16x16x32_f16 v[52:55], v[176:179], v[144:147], v[52:55]
	v_mfma_f32_16x16x32_f16 v[48:51], v[184:187], v[144:147], v[48:51]
	v_mfma_f32_16x16x32_f16 v[36:39], v[176:179], v[152:155], v[36:39]
	v_mfma_f32_16x16x32_f16 v[32:35], v[184:187], v[152:155], v[32:35]
	v_mfma_f32_16x16x32_f16 v[20:23], v[176:179], v[160:163], v[20:23]
	v_mfma_f32_16x16x32_f16 v[16:19], v[184:187], v[160:163], v[16:19]
	v_mfma_f32_16x16x32_f16 v[4:7], v[176:179], v[168:171], v[4:7]
	v_mfma_f32_16x16x32_f16 v[0:3], v[184:187], v[168:171], v[0:3]
	v_mfma_f32_16x16x32_f16 v[52:55], v[180:183], v[148:151], v[52:55]
	v_mfma_f32_16x16x32_f16 v[48:51], v[188:191], v[148:151], v[48:51]
	v_mfma_f32_16x16x32_f16 v[36:39], v[180:183], v[156:159], v[36:39]
	v_mfma_f32_16x16x32_f16 v[32:35], v[188:191], v[156:159], v[32:35]
	v_mfma_f32_16x16x32_f16 v[20:23], v[180:183], v[164:167], v[20:23]
	v_mfma_f32_16x16x32_f16 v[16:19], v[188:191], v[164:167], v[16:19]
	v_mfma_f32_16x16x32_f16 v[4:7], v[180:183], v[172:175], v[4:7]
	v_mfma_f32_16x16x32_f16 v[0:3], v[188:191], v[172:175], v[0:3]
	s_add_u32 s0, s0, 0x100
	s_addc_u32 s1, s1, 0
	s_add_u32 s27, s27, 0x100
	s_addc_u32 s33, s33, 0
	s_cmp_ge_u32 s38, s64
	s_mov_b32 s34, s38
	s_barrier
	s_cbranch_scc0 .LBB0_762
	s_setprio 0
	s_lshl_b32 s0, s84, 8
	s_or_b32 s27, s0, s65
	v_lshl_add_u32 v240, s30, 8, v200
	v_or_b32_e32 v216, s27, v202
	s_cmp_eq_u32 s93, 3
	s_cbranch_scc1 .Lst16_fast
	s_cmp_eq_u32 s93, 1
	s_cbranch_scc0 .Llora_no
	s_lshr_b32 s0, s84, 2
	s_cmp_lt_u32 s0, 2
	s_cbranch_scc1 .Llora_fast
